# mLSTM output phase: three over-conservative vmcnt(0) waits replaced by counted waits (gate loads only / leave next-unit prefetch and the 16 output stores in flight), WAW-paranoia wait on wave 0 remove
# speedup vs baseline: 1.0044x; 1.0028x over previous
; __device__ __forceinline__ bf16_t f2bf(float f) { return (bf16_t)(cvtpk(f, 0.f) & 0xffffu); }
; __device__ __forceinline__ float fsigmoid(float x) { return __builtin_amdgcn_rcpf(1.f + __builtin_amdgcn_exp2f(-x * LOG2E)); }
; #define MLO_LOADV(UU) do { const int _bh = (UU) >> 8, _c = (UU) & 255, _b = _bh >> 2, _h = _bh & 3; const size_t _r0 = (size_t)_b * SEQ + _c * 64; \
;         _Pragma("unroll") for (int i = 0; i < 2; ++i) { const int id = tid + 512 * i, row = id >> 4, ch = id & 15; rv[i] = *(const u32x4*)(proj + (_r0 + row) * NIN + 2560 + _h * 128 + 8 * ch); } } while (0)
; __device__ __forceinline__ void ml_out_phase(const Args& a, LAS unsigned char* lds) {
;     ...
;     MLO_LOAD(unit); MLO_LOADV(unit);
;     const float g0 = a.in[15][lane], g1 = a.in[15][lane + 64];
;     ...
;     if (unit + G < 2048) MLO_LOADV(unit + G);
;     { bf16_t* mix = (bf16_t*)(ws + WS_XB);
; #pragma unroll
;       for (int i = 0; i < 8; ++i) { const int jr = 8 * wid + i; const float x0 = Hs[jr * 132 + lane], x1 = Hs[jr * 132 + lane + 64];
;           const float mean = wave_sum(x0 + x1) * (1.f / 128.f); const float d0 = x0 - mean, d1 = x1 - mean;
;           const float rstd = 1.f / sqrtf(wave_sum(d0 * d0 + d1 * d1) * (1.f / 128.f) + LN_EPS);
;           const float o0 = __uint_as_float(ogp[i] << 16), o1 = __uint_as_float(ogp[i] & 0xffff0000u);
;           bf16_t* mp = mix + (row0 + jr) * D + 512 + h * 128;
;           mp[lane] = f2bf(d0 * rstd * g0 * fsigmoid(o0)); mp[lane + 64] = f2bf(d1 * rstd * g1 * fsigmoid(o1)); } }
.LBB0_614:
	s_or_b64 exec, exec, s[4:5]
	v_and_b32_e32 v6, 63, v1
	s_add_u32 s76, s86, 0x7000000
	s_addc_u32 s77, s87, 0
	v_lshlrev_b32_e32 v6, 2, v6
	s_waitcnt lgkmcnt(0)
	global_load_dword v122, v6, s[50:51]
	global_load_dword v123, v6, s[50:51] offset:256
	s_movk_i32 s90, 0x1c00
	v_mov_b64_e32 v[6:7], s[76:77]
	v_mad_u64_u32 v[8:9], s[0:1], v4, s90, v[6:7]
	v_mov_b32_e32 v4, v9
	v_mad_u64_u32 v[4:5], s[0:1], v5, s90, v[4:5]
	v_mad_u64_u32 v[6:7], s[0:1], v2, s90, v[6:7]
	v_mov_b32_e32 v9, v4
	s_lshl_b32 s82, s8, 1
	s_mov_b32 s83, 0
	v_mov_b32_e32 v2, v7
	v_lshl_add_u64 v[4:5], v[8:9], 0, s[82:83]
	v_mov_b32_e32 v109, 0
	v_mov_b32_e32 v108, v106
	v_mad_u64_u32 v[2:3], s[0:1], v3, s90, v[2:3]
	v_lshl_add_u64 v[4:5], v[4:5], 0, v[108:109]
	s_movk_i32 s91, 0x1000
	v_mov_b32_e32 v7, v2
	v_add_co_u32_e32 v4, vcc, s91, v4
	v_lshl_add_u64 v[2:3], v[6:7], 0, s[82:83]
	s_lshl_b64 s[0:1], s[92:93], 2
	v_addc_co_u32_e32 v5, vcc, 0, v5, vcc
	v_lshl_add_u64 v[2:3], v[2:3], 0, v[108:109]
	s_add_u32 s0, s89, s0
	v_add_co_u32_e32 v2, vcc, s91, v2
	s_addc_u32 s1, s33, s1
	v_mov_b32_e32 v106, 0x4000
	v_addc_co_u32_e32 v3, vcc, 0, v3, vcc
	global_load_dwordx4 v[70:73], v[4:5], off offset:1024
	global_load_dwordx4 v[66:69], v[2:3], off offset:1024
	global_load_dword v149, v106, s[0:1]
	s_add_u32 s0, s86, 0x2dfff00
	v_writelane_b32 v238, s0, 30
	s_addc_u32 s0, s87, 0
	v_writelane_b32 v238, s0, 31
	s_add_u32 s0, s86, 0x2d00000
	s_addc_u32 s1, s87, 0
	v_writelane_b32 v238, s0, 32
	v_mbcnt_lo_u32_b32 v2, -1, 0
	s_lshl_b32 s93, s88, 6
	v_writelane_b32 v238, s1, 33
	s_movk_i32 s70, 0x110
	s_add_i32 s0, 0, 0x1de00
	s_add_i32 s73, 0, 0x1e000
	s_add_i32 s78, 0, 0x15800
	s_movk_i32 s79, 0x210
	v_mov_b32_e32 v124, 0x3727c5ac
	s_mov_b32 s80, 0xf800000
	v_mov_b32_e32 v125, 0x260
	s_mov_b64 s[94:95], 0x3000400
	s_mov_b32 s81, 0x3000000
	v_mov_b32_e32 v126, 0xff800000
	v_mbcnt_hi_u32_b32 v127, -1, v2
	s_mov_b32 s2, s92
	v_writelane_b32 v238, s0, 34
	s_waitcnt vmcnt(0)
	s_branch .LBB0_616
.LBB0_615:
	v_lshl_add_u32 v2, v136, 2, s78
	s_movk_i32 s4, 0x1080
	v_mad_u64_u32 v[4:5], s[4:5], v137, s4, v[2:3]
	ds_read2st64_b32 v[8:9], v4 offset1:1
	s_waitcnt vmcnt(8)
	v_lshlrev_b32_e32 v16, 16, v144
	v_lshlrev_b32_e32 v17, 16, v143
	v_lshlrev_b32_e32 v18, 16, v139
	v_lshlrev_b32_e32 v19, 16, v138
	s_waitcnt lgkmcnt(0)
	v_add_f32_e32 v3, v8, v9
	s_waitcnt vmcnt(8)
	v_lshlrev_b32_e32 v7, 16, v145
	v_mul_f32_e32 v7, 0xbfb8aa3b, v7
	v_add_f32_dpp v3, v3, v3 quad_perm:[1,0,3,2] row_mask:0xf bank_mask:0xf bound_ctrl:1
	v_exp_f32_e32 v7, v7
	s_mov_b32 s72, s3
	v_add_f32_dpp v3, v3, v3 quad_perm:[2,3,0,1] row_mask:0xf bank_mask:0xf bound_ctrl:1
	v_mov_b32_e32 v149, v129
	v_add_f32_e32 v7, 1.0, v7
	v_add_f32_dpp v3, v3, v3 row_half_mirror row_mask:0xf bank_mask:0xf bound_ctrl:1
	v_rcp_f32_e32 v7, v7
	s_nop 0
	v_add_f32_dpp v3, v3, v3 row_mirror row_mask:0xf bank_mask:0xf bound_ctrl:1
	v_mov_b32_e32 v4, v3
	s_nop 1
	v_permlane16_swap_b32_e32 v3, v4
	v_add_f32_e32 v3, v3, v4
	v_mov_b32_e32 v4, v3
	s_nop 1
	v_permlane32_swap_b32_e32 v3, v4
	v_add_f32_e32 v3, v3, v4
	v_fmac_f32_e32 v9, 0xbc000000, v3
	v_fmamk_f32 v8, v3, 0xbc000000, v8
	v_mul_f32_e32 v3, v9, v9
	v_fmac_f32_e32 v3, v8, v8
	s_nop 1
	v_add_f32_dpp v3, v3, v3 quad_perm:[1,0,3,2] row_mask:0xf bank_mask:0xf bound_ctrl:1
	s_nop 1
	v_add_f32_dpp v3, v3, v3 quad_perm:[2,3,0,1] row_mask:0xf bank_mask:0xf bound_ctrl:1
	s_nop 1
	v_add_f32_dpp v3, v3, v3 row_half_mirror row_mask:0xf bank_mask:0xf bound_ctrl:1
	s_nop 1
	v_add_f32_dpp v3, v3, v3 row_mirror row_mask:0xf bank_mask:0xf bound_ctrl:1
	v_mov_b32_e32 v4, v3
	s_nop 1
	v_permlane16_swap_b32_e32 v3, v4
	v_add_f32_e32 v3, v3, v4
	v_mov_b32_e32 v4, v3
	s_nop 1
	v_permlane32_swap_b32_e32 v3, v4
	v_add_f32_e32 v3, v3, v4
	v_fmamk_f32 v3, v3, 0x3c000000, v124
	v_mul_f32_e32 v4, 0x4f800000, v3
	v_cmp_gt_f32_e32 vcc, s80, v3
	s_nop 1
	v_cndmask_b32_e32 v3, v3, v4, vcc
	v_sqrt_f32_e32 v4, v3
	s_nop 0
	v_add_u32_e32 v5, -1, v4
	v_fma_f32 v6, -v5, v4, v3
	v_cmp_ge_f32_e64 s[4:5], 0, v6
	v_add_u32_e32 v6, 1, v4
	s_nop 0
	v_cndmask_b32_e64 v5, v4, v5, s[4:5]
	v_fma_f32 v4, -v6, v4, v3
	v_cmp_lt_f32_e64 s[4:5], 0, v4
	s_nop 1
	v_cndmask_b32_e64 v4, v5, v6, s[4:5]
	v_mul_f32_e32 v5, 0x37800000, v4
	v_cndmask_b32_e32 v4, v4, v5, vcc
	v_cmp_class_f32_e32 vcc, v3, v125
	v_lshlrev_b32_e32 v6, 16, v142
	v_mul_f32_e32 v6, 0xbfb8aa3b, v6
	v_cndmask_b32_e32 v3, v4, v3, vcc
	v_div_scale_f32 v10, s[4:5], v3, v3, 1.0
	v_rcp_f32_e32 v11, v10
	v_lshlrev_b32_e32 v5, 16, v141
	v_lshlrev_b32_e32 v4, 16, v140
	v_mul_f32_e32 v4, 0xbfb8aa3b, v4
	v_fma_f32 v12, -v10, v11, 1.0
	v_fmac_f32_e32 v11, v12, v11
	v_div_scale_f32 v12, vcc, 1.0, v3, 1.0
	v_mul_f32_e32 v13, v12, v11
	v_fma_f32 v14, -v10, v13, v12
	v_fmac_f32_e32 v13, v14, v11
	v_fma_f32 v10, -v10, v13, v12
	v_div_fmas_f32 v10, v10, v11, v13
	v_lshlrev_b32_e32 v11, 16, v135
	v_mul_f32_e32 v11, 0xbfb8aa3b, v11
	v_exp_f32_e32 v12, v11
	v_div_fixup_f32 v20, v10, v3, 1.0
	v_mul_f32_e32 v8, v8, v20
	v_mul_f32_e32 v8, v122, v8
	v_add_f32_e32 v3, 1.0, v12
	v_rcp_f32_e32 v3, v3
	v_lshlrev_b64 v[10:11], 11, v[112:113]
	v_lshl_add_u64 v[10:11], s[86:87], 0, v[10:11]
	v_lshl_add_u64 v[10:11], v[10:11], 0, s[82:83]
	v_mul_f32_e32 v3, v3, v8
	v_or_b32_e32 v8, 1, v110
	v_cvt_pk_bf16_f32 v21, v3, s0
	v_mad_u64_u32 v[2:3], s[4:5], v8, s79, v[2:3]
	ds_read2st64_b32 v[14:15], v2 offset1:1
	v_lshl_add_u64 v[10:11], v[10:11], 0, v[108:109]
	v_lshl_add_u64 v[12:13], v[10:11], 0, s[94:95]
	v_add_co_u32_e32 v10, vcc, s81, v10
	v_mul_f32_e32 v3, v9, v20
	s_nop 0
	v_addc_co_u32_e32 v11, vcc, 0, v11, vcc
	global_store_short v[10:11], v21, off offset:1024
	s_waitcnt lgkmcnt(0)
; __device__ __forceinline__ bf16_t f2bf(float f) { return (bf16_t)(cvtpk(f, 0.f) & 0xffffu); }
; __device__ __forceinline__ float fsigmoid(float x) { return __builtin_amdgcn_rcpf(1.f + __builtin_amdgcn_exp2f(-x * LOG2E)); }
; __device__ __forceinline__ void ml_out_phase(const Args& a, LAS unsigned char* lds) {
;     ...
;       for (int i = 0; i < 8; ++i) { const int jr = 8 * wid + i; const float x0 = Hs[jr * 132 + lane], x1 = Hs[jr * 132 + lane + 64];
;           const float mean = wave_sum(x0 + x1) * (1.f / 128.f); const float d0 = x0 - mean, d1 = x1 - mean;
;           const float rstd = 1.f / sqrtf(wave_sum(d0 * d0 + d1 * d1) * (1.f / 128.f) + LN_EPS);
;           const float o0 = __uint_as_float(ogp[i] << 16), o1 = __uint_as_float(ogp[i] & 0xffff0000u);
;           bf16_t* mp = mix + (row0 + jr) * D + 512 + h * 128;
;           mp[lane] = f2bf(d0 * rstd * g0 * fsigmoid(o0)); mp[lane + 64] = f2bf(d1 * rstd * g1 * fsigmoid(o1)); } }
	v_add_f32_e32 v10, v14, v15
	v_mul_f32_e32 v9, 0xbfb8aa3b, v16
	v_exp_f32_e32 v9, v9
	v_add_f32_dpp v10, v10, v10 quad_perm:[1,0,3,2] row_mask:0xf bank_mask:0xf bound_ctrl:1
	v_mul_f32_e32 v3, v123, v3
	v_add_f32_e32 v9, 1.0, v9
	v_add_f32_dpp v10, v10, v10 quad_perm:[2,3,0,1] row_mask:0xf bank_mask:0xf bound_ctrl:1
	v_rcp_f32_e32 v9, v9
	s_nop 0
	v_add_f32_dpp v10, v10, v10 row_half_mirror row_mask:0xf bank_mask:0xf bound_ctrl:1
	v_mul_f32_e32 v3, v9, v3
	s_nop 0
	v_add_f32_dpp v10, v10, v10 row_mirror row_mask:0xf bank_mask:0xf bound_ctrl:1
	v_mov_b32_e32 v11, v10
	s_nop 1
	v_permlane16_swap_b32_e32 v10, v11
	v_add_f32_e32 v10, v10, v11
	v_mov_b32_e32 v11, v10
	s_nop 1
	v_permlane32_swap_b32_e32 v10, v11
	v_add_f32_e32 v10, v10, v11
	v_fmac_f32_e32 v15, 0xbc000000, v10
	v_fmamk_f32 v11, v10, 0xbc000000, v14
	v_mul_f32_e32 v10, v15, v15
	v_fmac_f32_e32 v10, v11, v11
	v_cvt_pk_bf16_f32 v3, v3, s0
	global_store_short v[12:13], v3, off offset:128
	v_add_f32_dpp v10, v10, v10 quad_perm:[1,0,3,2] row_mask:0xf bank_mask:0xf bound_ctrl:1
	s_nop 1
	v_add_f32_dpp v10, v10, v10 quad_perm:[2,3,0,1] row_mask:0xf bank_mask:0xf bound_ctrl:1
	s_nop 1
	v_add_f32_dpp v10, v10, v10 row_half_mirror row_mask:0xf bank_mask:0xf bound_ctrl:1
	s_nop 1
	v_add_f32_dpp v10, v10, v10 row_mirror row_mask:0xf bank_mask:0xf bound_ctrl:1
	v_mov_b32_e32 v14, v10
	s_nop 1
	v_permlane16_swap_b32_e32 v10, v14
	v_add_f32_e32 v10, v10, v14
	v_mov_b32_e32 v14, v10
	s_nop 1
	v_permlane32_swap_b32_e32 v10, v14
	v_add_f32_e32 v10, v10, v14
	v_fmamk_f32 v10, v10, 0x3c000000, v124
	v_mul_f32_e32 v14, 0x4f800000, v10
	v_cmp_gt_f32_e32 vcc, s80, v10
	s_nop 1
	v_cndmask_b32_e32 v10, v10, v14, vcc
	v_sqrt_f32_e32 v14, v10
	s_nop 0
	v_add_u32_e32 v16, -1, v14
	v_fma_f32 v20, -v16, v14, v10
	v_cmp_ge_f32_e64 s[4:5], 0, v20
	v_add_u32_e32 v20, 1, v14
	s_nop 0
	v_cndmask_b32_e64 v16, v14, v16, s[4:5]
	v_fma_f32 v14, -v20, v14, v10
	v_cmp_lt_f32_e64 s[4:5], 0, v14
	s_nop 1
	v_cndmask_b32_e64 v14, v16, v20, s[4:5]
	v_mul_f32_e32 v16, 0x37800000, v14
	v_cndmask_b32_e32 v14, v14, v16, vcc
	v_cmp_class_f32_e32 vcc, v10, v125
	s_nop 1
	v_cndmask_b32_e32 v10, v14, v10, vcc
	v_div_scale_f32 v14, s[4:5], v10, v10, 1.0
	v_rcp_f32_e32 v16, v14
	s_nop 0
	v_fma_f32 v3, -v14, v16, 1.0
	v_fmac_f32_e32 v16, v3, v16
	v_div_scale_f32 v3, vcc, 1.0, v10, 1.0
	v_mul_f32_e32 v9, v3, v16
	v_fma_f32 v12, -v14, v9, v3
	v_fmac_f32_e32 v9, v12, v16
	v_fma_f32 v3, -v14, v9, v3
	v_div_fmas_f32 v3, v3, v16, v9
	v_div_fixup_f32 v3, v3, v10, 1.0
	v_lshlrev_b32_e32 v10, 16, v134
	v_mul_f32_e32 v10, 0xbfb8aa3b, v10
	v_exp_f32_e32 v10, v10
	v_ashrrev_i32_e32 v9, 31, v8
	v_lshl_add_u64 v[8:9], s[74:75], 0, v[8:9]
	v_lshlrev_b64 v[8:9], 11, v[8:9]
	v_add_f32_e32 v10, 1.0, v10
	v_rcp_f32_e32 v10, v10
	v_mul_f32_e32 v12, 0xbfb8aa3b, v17
	v_lshl_add_u64 v[8:9], s[86:87], 0, v[8:9]
	v_mul_f32_e32 v11, v11, v3
	v_exp_f32_e32 v16, v12
	ds_read2_b32 v[12:13], v2 offset0:132 offset1:196
	v_lshl_add_u64 v[8:9], v[8:9], 0, s[82:83]
	v_mul_f32_e32 v11, v122, v11
	v_mul_f32_e32 v10, v10, v11
	v_lshl_add_u64 v[8:9], v[8:9], 0, v[108:109]
	v_cvt_pk_bf16_f32 v14, v10, s0
	v_lshl_add_u64 v[10:11], v[8:9], 0, s[94:95]
	v_add_co_u32_e32 v8, vcc, s81, v8
	v_mul_f32_e32 v3, v15, v3
	s_nop 0
	v_addc_co_u32_e32 v9, vcc, 0, v9, vcc
	global_store_short v[8:9], v14, off offset:1024
	s_waitcnt lgkmcnt(0)
	v_add_f32_e32 v9, v12, v13
	v_add_f32_e32 v8, 1.0, v16
	v_rcp_f32_e32 v8, v8
	v_add_f32_dpp v9, v9, v9 quad_perm:[1,0,3,2] row_mask:0xf bank_mask:0xf bound_ctrl:1
	v_mul_f32_e32 v3, v123, v3
	v_mul_f32_e32 v3, v8, v3
	v_add_f32_dpp v9, v9, v9 quad_perm:[2,3,0,1] row_mask:0xf bank_mask:0xf bound_ctrl:1
	v_cvt_pk_bf16_f32 v3, v3, s0
	global_store_short v[10:11], v3, off offset:128
	v_add_f32_dpp v9, v9, v9 row_half_mirror row_mask:0xf bank_mask:0xf bound_ctrl:1
	s_nop 1
	v_add_f32_dpp v9, v9, v9 row_mirror row_mask:0xf bank_mask:0xf bound_ctrl:1
	v_mov_b32_e32 v14, v9
	s_nop 1
	v_permlane16_swap_b32_e32 v9, v14
	v_add_f32_e32 v9, v9, v14
	v_mov_b32_e32 v14, v9
	s_nop 1
	v_permlane32_swap_b32_e32 v9, v14
	v_add_f32_e32 v9, v9, v14
	v_fmac_f32_e32 v13, 0xbc000000, v9
	v_fmamk_f32 v12, v9, 0xbc000000, v12
	v_mul_f32_e32 v9, v13, v13
	v_fmac_f32_e32 v9, v12, v12
	s_nop 1
	v_add_f32_dpp v9, v9, v9 quad_perm:[1,0,3,2] row_mask:0xf bank_mask:0xf bound_ctrl:1
	s_nop 1
	v_add_f32_dpp v9, v9, v9 quad_perm:[2,3,0,1] row_mask:0xf bank_mask:0xf bound_ctrl:1
	s_nop 1
	v_add_f32_dpp v9, v9, v9 row_half_mirror row_mask:0xf bank_mask:0xf bound_ctrl:1
	s_nop 1
	v_add_f32_dpp v9, v9, v9 row_mirror row_mask:0xf bank_mask:0xf bound_ctrl:1
	v_mov_b32_e32 v14, v9
	s_nop 1
	v_permlane16_swap_b32_e32 v9, v14
	v_add_f32_e32 v9, v9, v14
	v_mov_b32_e32 v14, v9
	s_nop 1
	v_permlane32_swap_b32_e32 v9, v14
	v_add_f32_e32 v9, v9, v14
	v_fmamk_f32 v9, v9, 0x3c000000, v124
	v_mul_f32_e32 v14, 0x4f800000, v9
	v_cmp_gt_f32_e32 vcc, s80, v9
	s_nop 1
	v_cndmask_b32_e32 v9, v9, v14, vcc
	v_sqrt_f32_e32 v14, v9
	s_nop 0
	v_add_u32_e32 v8, -1, v14
	v_fma_f32 v15, -v8, v14, v9
	v_cmp_ge_f32_e64 s[4:5], 0, v15
	v_add_u32_e32 v15, 1, v14
	s_nop 0
	v_cndmask_b32_e64 v8, v14, v8, s[4:5]
	v_fma_f32 v14, -v15, v14, v9
	v_cmp_lt_f32_e64 s[4:5], 0, v14
	s_nop 1
	v_cndmask_b32_e64 v8, v8, v15, s[4:5]
	v_mul_f32_e32 v14, 0x37800000, v8
	v_cndmask_b32_e32 v8, v8, v14, vcc
	v_cmp_class_f32_e32 vcc, v9, v125
	s_nop 1
	v_cndmask_b32_e32 v9, v8, v9, vcc
	v_div_scale_f32 v14, s[4:5], v9, v9, 1.0
	v_rcp_f32_e32 v15, v14
	v_or_b32_e32 v8, 2, v110
	v_fma_f32 v3, -v14, v15, 1.0
	v_fmac_f32_e32 v15, v3, v15
	v_div_scale_f32 v3, vcc, 1.0, v9, 1.0
	v_mul_f32_e32 v10, v3, v15
	v_fma_f32 v11, -v14, v10, v3
	v_fmac_f32_e32 v10, v11, v15
	v_fma_f32 v3, -v14, v10, v3
	v_div_fmas_f32 v3, v3, v15, v10
	v_lshlrev_b32_e32 v10, 16, v133
	v_mul_f32_e32 v10, 0xbfb8aa3b, v10
	v_exp_f32_e32 v10, v10
	v_div_fixup_f32 v3, v3, v9, 1.0
	v_ashrrev_i32_e32 v9, 31, v8
	v_lshl_add_u64 v[8:9], s[74:75], 0, v[8:9]
	v_add_f32_e32 v10, 1.0, v10
	v_rcp_f32_e32 v10, v10
	v_mul_f32_e32 v14, 0xbfb8aa3b, v18
	v_lshlrev_b64 v[8:9], 11, v[8:9]
	v_exp_f32_e32 v16, v14
	v_add_u32_e32 v14, 32, v2
	v_lshl_add_u64 v[8:9], s[86:87], 0, v[8:9]
	v_mul_f32_e32 v11, v12, v3
	ds_read2st64_b32 v[14:15], v14 offset0:4 offset1:5
	v_lshl_add_u64 v[8:9], v[8:9], 0, s[82:83]
	v_mul_f32_e32 v11, v122, v11
	v_mul_f32_e32 v10, v10, v11
	v_lshl_add_u64 v[8:9], v[8:9], 0, v[108:109]
	v_cvt_pk_bf16_f32 v12, v10, s0
	v_lshl_add_u64 v[10:11], v[8:9], 0, s[94:95]
	v_add_co_u32_e32 v8, vcc, s81, v8
	v_mul_f32_e32 v3, v13, v3
	s_nop 0
	v_addc_co_u32_e32 v9, vcc, 0, v9, vcc
	global_store_short v[8:9], v12, off offset:1024
	s_waitcnt lgkmcnt(0)
; __device__ __forceinline__ bf16_t f2bf(float f) { return (bf16_t)(cvtpk(f, 0.f) & 0xffffu); }
; __device__ __forceinline__ float fsigmoid(float x) { return __builtin_amdgcn_rcpf(1.f + __builtin_amdgcn_exp2f(-x * LOG2E)); }
; __device__ __forceinline__ void ml_out_phase(const Args& a, LAS unsigned char* lds) {
;     ...
;       for (int i = 0; i < 8; ++i) { const int jr = 8 * wid + i; const float x0 = Hs[jr * 132 + lane], x1 = Hs[jr * 132 + lane + 64];
;           const float mean = wave_sum(x0 + x1) * (1.f / 128.f); const float d0 = x0 - mean, d1 = x1 - mean;
;           const float rstd = 1.f / sqrtf(wave_sum(d0 * d0 + d1 * d1) * (1.f / 128.f) + LN_EPS);
;           const float o0 = __uint_as_float(ogp[i] << 16), o1 = __uint_as_float(ogp[i] & 0xffff0000u);
;           bf16_t* mp = mix + (row0 + jr) * D + 512 + h * 128;
;           mp[lane] = f2bf(d0 * rstd * g0 * fsigmoid(o0)); mp[lane + 64] = f2bf(d1 * rstd * g1 * fsigmoid(o1)); } }
	v_add_f32_e32 v9, v14, v15
	v_add_f32_e32 v8, 1.0, v16
	v_rcp_f32_e32 v8, v8
	v_add_f32_dpp v9, v9, v9 quad_perm:[1,0,3,2] row_mask:0xf bank_mask:0xf bound_ctrl:1
	v_mul_f32_e32 v3, v123, v3
	v_mul_f32_e32 v3, v8, v3
	v_add_f32_dpp v9, v9, v9 quad_perm:[2,3,0,1] row_mask:0xf bank_mask:0xf bound_ctrl:1
	v_cvt_pk_bf16_f32 v3, v3, s0
	global_store_short v[10:11], v3, off offset:128
	v_add_f32_dpp v9, v9, v9 row_half_mirror row_mask:0xf bank_mask:0xf bound_ctrl:1
	s_nop 1
	v_add_f32_dpp v9, v9, v9 row_mirror row_mask:0xf bank_mask:0xf bound_ctrl:1
	v_mov_b32_e32 v12, v9
	s_nop 1
	v_permlane16_swap_b32_e32 v9, v12
	v_add_f32_e32 v9, v9, v12
	v_mov_b32_e32 v12, v9
	s_nop 1
	v_permlane32_swap_b32_e32 v9, v12
	v_add_f32_e32 v9, v9, v12
	v_fmac_f32_e32 v15, 0xbc000000, v9
	v_fmamk_f32 v12, v9, 0xbc000000, v14
	v_mul_f32_e32 v9, v15, v15
	v_fmac_f32_e32 v9, v12, v12
	s_nop 1
	v_add_f32_dpp v9, v9, v9 quad_perm:[1,0,3,2] row_mask:0xf bank_mask:0xf bound_ctrl:1
	s_nop 1
	v_add_f32_dpp v9, v9, v9 quad_perm:[2,3,0,1] row_mask:0xf bank_mask:0xf bound_ctrl:1
	s_nop 1
	v_add_f32_dpp v9, v9, v9 row_half_mirror row_mask:0xf bank_mask:0xf bound_ctrl:1
	s_nop 1
	v_add_f32_dpp v9, v9, v9 row_mirror row_mask:0xf bank_mask:0xf bound_ctrl:1
	v_mov_b32_e32 v14, v9
	s_nop 1
	v_permlane16_swap_b32_e32 v9, v14
	v_add_f32_e32 v9, v9, v14
	v_mov_b32_e32 v14, v9
	s_nop 1
	v_permlane32_swap_b32_e32 v9, v14
	v_add_f32_e32 v9, v9, v14
	v_fmamk_f32 v9, v9, 0x3c000000, v124
	v_mul_f32_e32 v14, 0x4f800000, v9
	v_cmp_gt_f32_e32 vcc, s80, v9
	s_nop 1
	v_cndmask_b32_e32 v9, v9, v14, vcc
	v_sqrt_f32_e32 v14, v9
	s_nop 0
	v_add_u32_e32 v8, -1, v14
	v_fma_f32 v13, -v8, v14, v9
	v_cmp_ge_f32_e64 s[4:5], 0, v13
	v_add_u32_e32 v13, 1, v14
	s_nop 0
	v_cndmask_b32_e64 v8, v14, v8, s[4:5]
	v_fma_f32 v14, -v13, v14, v9
	v_cmp_lt_f32_e64 s[4:5], 0, v14
	s_nop 1
	v_cndmask_b32_e64 v8, v8, v13, s[4:5]
	v_mul_f32_e32 v13, 0x37800000, v8
	v_cndmask_b32_e32 v8, v8, v13, vcc
	v_cmp_class_f32_e32 vcc, v9, v125
	s_nop 1
	v_cndmask_b32_e32 v9, v8, v9, vcc
	v_div_scale_f32 v13, s[4:5], v9, v9, 1.0
	v_rcp_f32_e32 v14, v13
	v_or_b32_e32 v8, 3, v110
	v_fma_f32 v3, -v13, v14, 1.0
	v_fmac_f32_e32 v14, v3, v14
	v_div_scale_f32 v3, vcc, 1.0, v9, 1.0
	v_mul_f32_e32 v10, v3, v14
	v_fma_f32 v11, -v13, v10, v3
	v_fmac_f32_e32 v10, v11, v14
	v_fma_f32 v3, -v13, v10, v3
	v_div_fmas_f32 v3, v3, v14, v10
	v_lshlrev_b32_e32 v10, 16, v132
	v_mul_f32_e32 v10, 0xbfb8aa3b, v10
	v_exp_f32_e32 v10, v10
	v_div_fixup_f32 v3, v3, v9, 1.0
	v_ashrrev_i32_e32 v9, 31, v8
	v_lshl_add_u64 v[8:9], s[74:75], 0, v[8:9]
	v_add_f32_e32 v10, 1.0, v10
	v_rcp_f32_e32 v10, v10
	v_mul_f32_e32 v11, v12, v3
	v_mul_f32_e32 v12, 0xbfb8aa3b, v19
	v_lshlrev_b64 v[8:9], 11, v[8:9]
	v_exp_f32_e32 v16, v12
	v_add_u32_e32 v12, 48, v2
	v_lshl_add_u64 v[8:9], s[86:87], 0, v[8:9]
	ds_read2st64_b32 v[12:13], v12 offset0:6 offset1:7
	v_lshl_add_u64 v[8:9], v[8:9], 0, s[82:83]
	v_mul_f32_e32 v11, v122, v11
	v_mul_f32_e32 v10, v10, v11
	v_lshl_add_u64 v[8:9], v[8:9], 0, v[108:109]
	v_cvt_pk_bf16_f32 v14, v10, s0
	v_lshl_add_u64 v[10:11], v[8:9], 0, s[94:95]
	v_add_co_u32_e32 v8, vcc, s81, v8
	v_mul_f32_e32 v3, v15, v3
	s_nop 0
	v_addc_co_u32_e32 v9, vcc, 0, v9, vcc
	global_store_short v[8:9], v14, off offset:1024
	s_waitcnt lgkmcnt(0)
	v_add_f32_e32 v9, v12, v13
	v_add_f32_e32 v8, 1.0, v16
	v_rcp_f32_e32 v8, v8
	v_add_f32_dpp v9, v9, v9 quad_perm:[1,0,3,2] row_mask:0xf bank_mask:0xf bound_ctrl:1
	v_mul_f32_e32 v3, v123, v3
	v_mul_f32_e32 v3, v8, v3
	v_add_f32_dpp v9, v9, v9 quad_perm:[2,3,0,1] row_mask:0xf bank_mask:0xf bound_ctrl:1
	v_cvt_pk_bf16_f32 v3, v3, s0
	global_store_short v[10:11], v3, off offset:128
	v_add_f32_dpp v9, v9, v9 row_half_mirror row_mask:0xf bank_mask:0xf bound_ctrl:1
	s_nop 1
	v_add_f32_dpp v9, v9, v9 row_mirror row_mask:0xf bank_mask:0xf bound_ctrl:1
	v_mov_b32_e32 v14, v9
	s_nop 1
	v_permlane16_swap_b32_e32 v9, v14
	v_add_f32_e32 v9, v9, v14
	v_mov_b32_e32 v14, v9
	s_nop 1
	v_permlane32_swap_b32_e32 v9, v14
	v_add_f32_e32 v9, v9, v14
	v_fmac_f32_e32 v13, 0xbc000000, v9
	v_fmamk_f32 v12, v9, 0xbc000000, v12
	v_mul_f32_e32 v9, v13, v13
	v_fmac_f32_e32 v9, v12, v12
	s_nop 1
	v_add_f32_dpp v9, v9, v9 quad_perm:[1,0,3,2] row_mask:0xf bank_mask:0xf bound_ctrl:1
	s_nop 1
	v_add_f32_dpp v9, v9, v9 quad_perm:[2,3,0,1] row_mask:0xf bank_mask:0xf bound_ctrl:1
	s_nop 1
	v_add_f32_dpp v9, v9, v9 row_half_mirror row_mask:0xf bank_mask:0xf bound_ctrl:1
	s_nop 1
	v_add_f32_dpp v9, v9, v9 row_mirror row_mask:0xf bank_mask:0xf bound_ctrl:1
	v_mov_b32_e32 v14, v9
	s_nop 1
	v_permlane16_swap_b32_e32 v9, v14
	v_add_f32_e32 v9, v9, v14
	v_mov_b32_e32 v14, v9
	s_nop 1
	v_permlane32_swap_b32_e32 v9, v14
	v_add_f32_e32 v9, v9, v14
	v_fmamk_f32 v9, v9, 0x3c000000, v124
	v_mul_f32_e32 v14, 0x4f800000, v9
	v_cmp_gt_f32_e32 vcc, s80, v9
	s_nop 1
	v_cndmask_b32_e32 v9, v9, v14, vcc
	v_sqrt_f32_e32 v14, v9
	s_nop 0
	v_add_u32_e32 v8, -1, v14
	v_fma_f32 v15, -v8, v14, v9
	v_cmp_ge_f32_e64 s[4:5], 0, v15
	v_add_u32_e32 v15, 1, v14
	s_nop 0
	v_cndmask_b32_e64 v8, v14, v8, s[4:5]
	v_fma_f32 v14, -v15, v14, v9
	v_cmp_lt_f32_e64 s[4:5], 0, v14
	s_nop 1
	v_cndmask_b32_e64 v8, v8, v15, s[4:5]
	v_mul_f32_e32 v14, 0x37800000, v8
	v_cndmask_b32_e32 v8, v8, v14, vcc
	v_cmp_class_f32_e32 vcc, v9, v125
	s_nop 1
	v_cndmask_b32_e32 v9, v8, v9, vcc
	v_div_scale_f32 v14, s[4:5], v9, v9, 1.0
	v_rcp_f32_e32 v15, v14
	v_or_b32_e32 v8, 4, v110
	v_fma_f32 v3, -v14, v15, 1.0
	v_fmac_f32_e32 v15, v3, v15
	v_div_scale_f32 v3, vcc, 1.0, v9, 1.0
	v_mul_f32_e32 v10, v3, v15
	v_fma_f32 v11, -v14, v10, v3
	v_fmac_f32_e32 v10, v11, v15
	v_fma_f32 v3, -v14, v10, v3
	v_div_fmas_f32 v3, v3, v15, v10
	v_lshlrev_b32_e32 v10, 16, v131
	v_mul_f32_e32 v10, 0xbfb8aa3b, v10
	v_exp_f32_e32 v10, v10
	v_div_fixup_f32 v3, v3, v9, 1.0
	v_ashrrev_i32_e32 v9, 31, v8
	v_lshl_add_u64 v[8:9], s[74:75], 0, v[8:9]
	v_add_f32_e32 v10, 1.0, v10
	v_rcp_f32_e32 v10, v10
	v_lshlrev_b64 v[8:9], 11, v[8:9]
	v_add_u32_e32 v14, 64, v2
	v_lshl_add_u64 v[8:9], s[86:87], 0, v[8:9]
	v_mul_f32_e32 v11, v12, v3
	ds_read2st64_b32 v[14:15], v14 offset0:8 offset1:9
	v_lshl_add_u64 v[8:9], v[8:9], 0, s[82:83]
	v_mul_f32_e32 v11, v122, v11
	v_mul_f32_e32 v10, v10, v11
	v_lshl_add_u64 v[8:9], v[8:9], 0, v[108:109]
	v_cvt_pk_bf16_f32 v12, v10, s0
	v_lshl_add_u64 v[10:11], v[8:9], 0, s[94:95]
	v_add_co_u32_e32 v8, vcc, s81, v8
	v_mul_f32_e32 v3, v13, v3
	s_nop 0
	v_addc_co_u32_e32 v9, vcc, 0, v9, vcc
	global_store_short v[8:9], v12, off offset:1024
	s_waitcnt lgkmcnt(0)
; __device__ __forceinline__ bf16_t f2bf(float f) { return (bf16_t)(cvtpk(f, 0.f) & 0xffffu); }
; __device__ __forceinline__ float fsigmoid(float x) { return __builtin_amdgcn_rcpf(1.f + __builtin_amdgcn_exp2f(-x * LOG2E)); }
; __device__ __forceinline__ void ml_out_phase(const Args& a, LAS unsigned char* lds) {
;     ...
;       for (int i = 0; i < 8; ++i) { const int jr = 8 * wid + i; const float x0 = Hs[jr * 132 + lane], x1 = Hs[jr * 132 + lane + 64];
;           const float mean = wave_sum(x0 + x1) * (1.f / 128.f); const float d0 = x0 - mean, d1 = x1 - mean;
;           const float rstd = 1.f / sqrtf(wave_sum(d0 * d0 + d1 * d1) * (1.f / 128.f) + LN_EPS);
;           const float o0 = __uint_as_float(ogp[i] << 16), o1 = __uint_as_float(ogp[i] & 0xffff0000u);
;           bf16_t* mp = mix + (row0 + jr) * D + 512 + h * 128;
;           mp[lane] = f2bf(d0 * rstd * g0 * fsigmoid(o0)); mp[lane + 64] = f2bf(d1 * rstd * g1 * fsigmoid(o1)); } }
	v_add_f32_e32 v8, v14, v15
	v_mul_f32_e32 v3, v123, v3
	v_mul_f32_e32 v3, v7, v3
	v_add_f32_dpp v8, v8, v8 quad_perm:[1,0,3,2] row_mask:0xf bank_mask:0xf bound_ctrl:1
	v_cvt_pk_bf16_f32 v3, v3, s0
	global_store_short v[10:11], v3, off offset:128
	v_add_f32_dpp v8, v8, v8 quad_perm:[2,3,0,1] row_mask:0xf bank_mask:0xf bound_ctrl:1
	s_nop 1
	v_add_f32_dpp v8, v8, v8 row_half_mirror row_mask:0xf bank_mask:0xf bound_ctrl:1
	s_nop 1
	v_add_f32_dpp v8, v8, v8 row_mirror row_mask:0xf bank_mask:0xf bound_ctrl:1
	v_mov_b32_e32 v9, v8
	s_nop 1
	v_permlane16_swap_b32_e32 v8, v9
	v_add_f32_e32 v8, v8, v9
	v_mov_b32_e32 v9, v8
	s_nop 1
	v_permlane32_swap_b32_e32 v8, v9
	v_add_f32_e32 v8, v8, v9
	v_fmac_f32_e32 v15, 0xbc000000, v8
	v_fmamk_f32 v12, v8, 0xbc000000, v14
	v_mul_f32_e32 v8, v15, v15
	v_fmac_f32_e32 v8, v12, v12
	s_nop 1
	v_add_f32_dpp v8, v8, v8 quad_perm:[1,0,3,2] row_mask:0xf bank_mask:0xf bound_ctrl:1
	s_nop 1
	v_add_f32_dpp v8, v8, v8 quad_perm:[2,3,0,1] row_mask:0xf bank_mask:0xf bound_ctrl:1
	s_nop 1
	v_add_f32_dpp v8, v8, v8 row_half_mirror row_mask:0xf bank_mask:0xf bound_ctrl:1
	s_nop 1
	v_add_f32_dpp v8, v8, v8 row_mirror row_mask:0xf bank_mask:0xf bound_ctrl:1
	v_mov_b32_e32 v9, v8
	s_nop 1
	v_permlane16_swap_b32_e32 v8, v9
	v_add_f32_e32 v8, v8, v9
	v_mov_b32_e32 v9, v8
	s_nop 1
	v_permlane32_swap_b32_e32 v8, v9
	v_add_f32_e32 v8, v8, v9
	v_fmamk_f32 v8, v8, 0x3c000000, v124
	v_mul_f32_e32 v9, 0x4f800000, v8
	v_cmp_gt_f32_e32 vcc, s80, v8
	s_nop 1
	v_cndmask_b32_e32 v8, v8, v9, vcc
	v_sqrt_f32_e32 v9, v8
	s_nop 0
	v_add_u32_e32 v7, -1, v9
	v_fma_f32 v13, -v7, v9, v8
	v_cmp_ge_f32_e64 s[4:5], 0, v13
	v_add_u32_e32 v13, 1, v9
	s_nop 0
	v_cndmask_b32_e64 v7, v9, v7, s[4:5]
	v_fma_f32 v9, -v13, v9, v8
	v_cmp_lt_f32_e64 s[4:5], 0, v9
	s_nop 1
	v_cndmask_b32_e64 v7, v7, v13, s[4:5]
	v_mul_f32_e32 v9, 0x37800000, v7
	v_cndmask_b32_e32 v7, v7, v9, vcc
	v_cmp_class_f32_e32 vcc, v8, v125
	s_nop 1
	v_cndmask_b32_e32 v7, v7, v8, vcc
	v_div_scale_f32 v9, s[4:5], v7, v7, 1.0
	v_rcp_f32_e32 v13, v9
	v_or_b32_e32 v8, 5, v110
	v_fma_f32 v3, -v9, v13, 1.0
	v_fmac_f32_e32 v13, v3, v13
	v_div_scale_f32 v3, vcc, 1.0, v7, 1.0
	v_mul_f32_e32 v10, v3, v13
	v_fma_f32 v11, -v9, v10, v3
	v_fmac_f32_e32 v10, v11, v13
	v_fma_f32 v3, -v9, v10, v3
	v_div_fmas_f32 v3, v3, v13, v10
	v_div_fixup_f32 v3, v3, v7, 1.0
	v_lshlrev_b32_e32 v7, 16, v130
	v_mul_f32_e32 v7, 0xbfb8aa3b, v7
	v_exp_f32_e32 v7, v7
	v_ashrrev_i32_e32 v9, 31, v8
	v_mul_f32_e32 v10, v12, v3
	v_lshl_add_u64 v[8:9], s[74:75], 0, v[8:9]
	v_add_f32_e32 v7, 1.0, v7
	v_rcp_f32_e32 v7, v7
	v_mul_f32_e32 v10, v122, v10
	v_lshlrev_b64 v[8:9], 11, v[8:9]
	v_exp_f32_e32 v13, v6
	v_mul_f32_e32 v7, v7, v10
	v_add_u32_e32 v6, 0x50, v2
	v_lshl_add_u64 v[8:9], s[86:87], 0, v[8:9]
	v_cvt_pk_bf16_f32 v12, v7, s0
	ds_read2st64_b32 v[6:7], v6 offset0:10 offset1:11
	v_lshl_add_u64 v[8:9], v[8:9], 0, s[82:83]
	v_lshl_add_u64 v[8:9], v[8:9], 0, v[108:109]
	v_lshl_add_u64 v[10:11], v[8:9], 0, s[94:95]
	v_add_co_u32_e32 v8, vcc, s81, v8
	v_mul_f32_e32 v3, v15, v3
	s_nop 0
	v_addc_co_u32_e32 v9, vcc, 0, v9, vcc
	global_store_short v[8:9], v12, off offset:1024
	s_waitcnt lgkmcnt(0)
	v_add_f32_e32 v9, v6, v7
	v_add_f32_e32 v8, 1.0, v13
	v_rcp_f32_e32 v8, v8
	v_add_f32_dpp v9, v9, v9 quad_perm:[1,0,3,2] row_mask:0xf bank_mask:0xf bound_ctrl:1
	v_mul_f32_e32 v3, v123, v3
	v_add_u32_e32 v2, 0x60, v2
	v_add_f32_dpp v9, v9, v9 quad_perm:[2,3,0,1] row_mask:0xf bank_mask:0xf bound_ctrl:1
	v_mul_f32_e32 v3, v8, v3
	v_cvt_pk_bf16_f32 v3, v3, s0
	v_add_f32_dpp v9, v9, v9 row_half_mirror row_mask:0xf bank_mask:0xf bound_ctrl:1
	global_store_short v[10:11], v3, off offset:128
	s_nop 0
	v_add_f32_dpp v9, v9, v9 row_mirror row_mask:0xf bank_mask:0xf bound_ctrl:1
	v_mov_b32_e32 v12, v9
	s_nop 1
	v_permlane16_swap_b32_e32 v9, v12
	v_add_f32_e32 v9, v9, v12
	v_mov_b32_e32 v12, v9
	s_nop 1
	v_permlane32_swap_b32_e32 v9, v12
	v_add_f32_e32 v9, v9, v12
	v_fmac_f32_e32 v7, 0xbc000000, v9
	v_fmamk_f32 v6, v9, 0xbc000000, v6
	v_mul_f32_e32 v9, v7, v7
	v_fmac_f32_e32 v9, v6, v6
	s_nop 1
	v_add_f32_dpp v9, v9, v9 quad_perm:[1,0,3,2] row_mask:0xf bank_mask:0xf bound_ctrl:1
	s_nop 1
	v_add_f32_dpp v9, v9, v9 quad_perm:[2,3,0,1] row_mask:0xf bank_mask:0xf bound_ctrl:1
	s_nop 1
	v_add_f32_dpp v9, v9, v9 row_half_mirror row_mask:0xf bank_mask:0xf bound_ctrl:1
	s_nop 1
	v_add_f32_dpp v9, v9, v9 row_mirror row_mask:0xf bank_mask:0xf bound_ctrl:1
	v_mov_b32_e32 v12, v9
	s_nop 1
	v_permlane16_swap_b32_e32 v9, v12
	v_add_f32_e32 v9, v9, v12
	v_mov_b32_e32 v12, v9
	s_nop 1
	v_permlane32_swap_b32_e32 v9, v12
	v_add_f32_e32 v9, v9, v12
	v_fmamk_f32 v9, v9, 0x3c000000, v124
	v_mul_f32_e32 v12, 0x4f800000, v9
	v_cmp_gt_f32_e32 vcc, s80, v9
	s_nop 1
	v_cndmask_b32_e32 v9, v9, v12, vcc
	v_sqrt_f32_e32 v12, v9
	s_nop 0
	v_add_u32_e32 v8, -1, v12
	v_fma_f32 v13, -v8, v12, v9
	v_cmp_ge_f32_e64 s[4:5], 0, v13
	v_add_u32_e32 v13, 1, v12
	s_nop 0
	v_cndmask_b32_e64 v8, v12, v8, s[4:5]
	v_fma_f32 v12, -v13, v12, v9
	v_cmp_lt_f32_e64 s[4:5], 0, v12
	s_nop 1
	v_cndmask_b32_e64 v8, v8, v13, s[4:5]
	v_mul_f32_e32 v12, 0x37800000, v8
	v_cndmask_b32_e32 v8, v8, v12, vcc
	v_cmp_class_f32_e32 vcc, v9, v125
	s_nop 1
	v_cndmask_b32_e32 v9, v8, v9, vcc
	v_div_scale_f32 v12, s[4:5], v9, v9, 1.0
	v_rcp_f32_e32 v13, v12
	v_or_b32_e32 v8, 6, v110
	v_fma_f32 v3, -v12, v13, 1.0
	v_fmac_f32_e32 v13, v3, v13
	v_div_scale_f32 v3, vcc, 1.0, v9, 1.0
	v_mul_f32_e32 v10, v3, v13
	v_fma_f32 v11, -v12, v10, v3
	v_fmac_f32_e32 v10, v11, v13
	v_fma_f32 v3, -v12, v10, v3
	v_div_fmas_f32 v3, v3, v13, v10
	v_div_fixup_f32 v12, v3, v9, 1.0
	v_lshlrev_b32_e32 v3, 16, v128
	v_mul_f32_e32 v3, 0xbfb8aa3b, v3
	v_exp_f32_e32 v3, v3
	v_mul_f32_e32 v6, v6, v12
	v_ashrrev_i32_e32 v9, 31, v8
	v_mul_f32_e32 v6, v122, v6
	v_add_f32_e32 v3, 1.0, v3
	v_rcp_f32_e32 v3, v3
	v_lshl_add_u64 v[8:9], s[74:75], 0, v[8:9]
	v_lshlrev_b64 v[8:9], 11, v[8:9]
	v_lshl_add_u64 v[8:9], s[86:87], 0, v[8:9]
	v_mul_f32_e32 v3, v3, v6
	v_cvt_pk_bf16_f32 v6, v3, s0
	v_mul_f32_e32 v3, 0xbfb8aa3b, v5
	v_exp_f32_e32 v5, v3
	ds_read2st64_b32 v[2:3], v2 offset0:12 offset1:13
	v_lshl_add_u64 v[8:9], v[8:9], 0, s[82:83]
	v_lshl_add_u64 v[8:9], v[8:9], 0, v[108:109]
	v_lshl_add_u64 v[10:11], v[8:9], 0, s[94:95]
	v_add_co_u32_e32 v8, vcc, s81, v8
	v_add_f32_e32 v5, 1.0, v5
	s_nop 0
	v_addc_co_u32_e32 v9, vcc, 0, v9, vcc
	global_store_short v[8:9], v6, off offset:1024
	s_waitcnt lgkmcnt(0)
; #define LAS __attribute__((address_space(3)))
; __device__ __forceinline__ bf16_t f2bf(float f) { return (bf16_t)(cvtpk(f, 0.f) & 0xffffu); }
; __device__ __forceinline__ float fsigmoid(float x) { return __builtin_amdgcn_rcpf(1.f + __builtin_amdgcn_exp2f(-x * LOG2E)); }
; __device__ __forceinline__ void ml_out_phase(const Args& a, LAS unsigned char* lds) {
;     ...
; #pragma unroll
;     for (int i = 0; i < 4; ++i) { const int id = tid + 512 * i, row = id >> 4, ch = id & 15;
;         *(LAS u32x4*)(Cs + row * 136 + 8 * ch) = rc[i]; }
; #pragma unroll
;     for (int i = 0; i < 2; ++i) { const int id = tid + 512 * i, row = id >> 4, ch = id & 15;
;         *(LAS u32x4*)(Qs + row * 136 + 8 * ch) = rq[i];
;         *(LAS u32x4*)(Ks + row * 136 + 8 * ch) = rk[i];
;         const unsigned uu[4] = {rv[i].x, rv[i].y, rv[i].z, rv[i].w};
; #pragma unroll
;         for (int e = 0; e < 4; ++e) { Vt[(8 * ch + 2 * e) * 72 + row] = (bf16_t)(uu[e] & 0xffffu); Vt[(8 * ch + 2 * e + 1) * 72 + row] = (bf16_t)(uu[e] >> 16); } }
;     if (tid < 64) { bs[tid] = rs0; lis[tid] = rs1; }
;     else if (tid < 192) { ns[tid - 64] = rs0; }
;     ...
;       for (int i = 0; i < 8; ++i) { const int jr = 8 * wid + i; const float x0 = Hs[jr * 132 + lane], x1 = Hs[jr * 132 + lane + 64];
;           const float mean = wave_sum(x0 + x1) * (1.f / 128.f); const float d0 = x0 - mean, d1 = x1 - mean;
;           const float rstd = 1.f / sqrtf(wave_sum(d0 * d0 + d1 * d1) * (1.f / 128.f) + LN_EPS);
;           const float o0 = __uint_as_float(ogp[i] << 16), o1 = __uint_as_float(ogp[i] & 0xffff0000u);
;           bf16_t* mp = mix + (row0 + jr) * D + 512 + h * 128;
;           mp[lane] = f2bf(d0 * rstd * g0 * fsigmoid(o0)); mp[lane + 64] = f2bf(d1 * rstd * g1 * fsigmoid(o1)); } }
	v_add_f32_e32 v6, v2, v3
	v_rcp_f32_e32 v5, v5
	v_mul_f32_e32 v7, v7, v12
	v_add_f32_dpp v6, v6, v6 quad_perm:[1,0,3,2] row_mask:0xf bank_mask:0xf bound_ctrl:1
	v_mul_f32_e32 v7, v123, v7
	v_mul_f32_e32 v5, v5, v7
	v_add_f32_dpp v6, v6, v6 quad_perm:[2,3,0,1] row_mask:0xf bank_mask:0xf bound_ctrl:1
	v_cvt_pk_bf16_f32 v5, v5, s0
	global_store_short v[10:11], v5, off offset:128
	v_add_f32_dpp v6, v6, v6 row_half_mirror row_mask:0xf bank_mask:0xf bound_ctrl:1
	s_nop 1
	v_add_f32_dpp v6, v6, v6 row_mirror row_mask:0xf bank_mask:0xf bound_ctrl:1
	v_mov_b32_e32 v8, v6
	s_nop 1
	v_permlane16_swap_b32_e32 v6, v8
	v_add_f32_e32 v6, v6, v8
	v_mov_b32_e32 v8, v6
	s_nop 1
	v_permlane32_swap_b32_e32 v6, v8
	v_add_f32_e32 v6, v6, v8
	v_fmac_f32_e32 v3, 0xbc000000, v6
	v_fmamk_f32 v2, v6, 0xbc000000, v2
	v_mul_f32_e32 v6, v3, v3
	v_fmac_f32_e32 v6, v2, v2
	s_nop 1
	v_add_f32_dpp v6, v6, v6 quad_perm:[1,0,3,2] row_mask:0xf bank_mask:0xf bound_ctrl:1
	s_nop 1
	v_add_f32_dpp v6, v6, v6 quad_perm:[2,3,0,1] row_mask:0xf bank_mask:0xf bound_ctrl:1
	s_nop 1
	v_add_f32_dpp v6, v6, v6 row_half_mirror row_mask:0xf bank_mask:0xf bound_ctrl:1
	s_nop 1
	v_add_f32_dpp v6, v6, v6 row_mirror row_mask:0xf bank_mask:0xf bound_ctrl:1
	v_mov_b32_e32 v8, v6
	s_nop 1
	v_permlane16_swap_b32_e32 v6, v8
	v_add_f32_e32 v6, v6, v8
	v_mov_b32_e32 v8, v6
	s_nop 1
	v_permlane32_swap_b32_e32 v6, v8
	v_add_f32_e32 v6, v6, v8
	v_fmamk_f32 v6, v6, 0x3c000000, v124
	v_mul_f32_e32 v8, 0x4f800000, v6
	v_cmp_gt_f32_e32 vcc, s80, v6
	s_nop 1
	v_cndmask_b32_e32 v6, v6, v8, vcc
	v_sqrt_f32_e32 v8, v6
	s_nop 0
	v_add_u32_e32 v7, -1, v8
	v_fma_f32 v9, -v7, v8, v6
	v_cmp_ge_f32_e64 s[4:5], 0, v9
	v_add_u32_e32 v9, 1, v8
	s_nop 0
	v_cndmask_b32_e64 v7, v8, v7, s[4:5]
	v_fma_f32 v8, -v9, v8, v6
	v_cmp_lt_f32_e64 s[4:5], 0, v8
	s_nop 1
	v_cndmask_b32_e64 v7, v7, v9, s[4:5]
	v_mul_f32_e32 v8, 0x37800000, v7
	v_cndmask_b32_e32 v7, v7, v8, vcc
	v_cmp_class_f32_e32 vcc, v6, v125
	s_nop 1
	v_cndmask_b32_e32 v7, v7, v6, vcc
	v_div_scale_f32 v8, s[4:5], v7, v7, 1.0
	v_rcp_f32_e32 v9, v8
	v_or_b32_e32 v6, 7, v110
	v_fma_f32 v5, -v8, v9, 1.0
	v_fmac_f32_e32 v9, v5, v9
	v_div_scale_f32 v5, vcc, 1.0, v7, 1.0
	v_mul_f32_e32 v10, v5, v9
	v_fma_f32 v11, -v8, v10, v5
	v_fmac_f32_e32 v10, v11, v9
	v_fma_f32 v5, -v8, v10, v5
	v_div_fmas_f32 v5, v5, v9, v10
	v_div_fixup_f32 v10, v5, v7, 1.0
	v_lshlrev_b32_e32 v5, 16, v111
	v_mul_f32_e32 v5, 0xbfb8aa3b, v5
	v_exp_f32_e32 v5, v5
	v_ashrrev_i32_e32 v7, 31, v6
	v_lshl_add_u64 v[6:7], s[74:75], 0, v[6:7]
	v_lshlrev_b64 v[6:7], 11, v[6:7]
	v_add_f32_e32 v5, 1.0, v5
	v_exp_f32_e32 v11, v4
	v_lshl_add_u64 v[6:7], s[86:87], 0, v[6:7]
	v_rcp_f32_e32 v5, v5
	v_lshl_add_u64 v[6:7], v[6:7], 0, s[82:83]
	v_mul_f32_e32 v2, v2, v10
	v_lshl_add_u64 v[6:7], v[6:7], 0, v[108:109]
	v_mul_f32_e32 v2, v122, v2
	v_lshl_add_u64 v[8:9], v[6:7], 0, s[94:95]
	v_add_co_u32_e32 v4, vcc, s81, v6
	v_add_f32_e32 v6, 1.0, v11
	v_mul_f32_e32 v2, v5, v2
	v_rcp_f32_e32 v6, v6
	v_cvt_pk_bf16_f32 v2, v2, s0
	v_addc_co_u32_e32 v5, vcc, 0, v7, vcc
	global_store_short v[4:5], v2, off offset:1024
	v_mul_f32_e32 v2, v3, v10
	v_mul_f32_e32 v2, v123, v2
	v_mul_f32_e32 v2, v6, v2
	v_cvt_pk_bf16_f32 v2, v2, s0
	global_store_short v[8:9], v2, off offset:128
	s_waitcnt lgkmcnt(0)
	s_barrier
	s_and_b64 vcc, exec, s[0:1]
	s_cbranch_vccz .LBB0_641
.LBB0_616:
	v_mov_b32_e32 v120, v1
	s_nop 0
	v_lshlrev_b32_e32 v2, 3, v120
	v_and_b32_e32 v3, 0x78, v2
	v_lshl_add_u32 v4, v3, 1, 0
	v_ashrrev_i32_e32 v116, 4, v120
	v_mad_u64_u32 v[6:7], s[0:1], v116, s70, v[4:5]
	v_add_u32_e32 v5, 0x200, v120
	v_ashrrev_i32_e32 v114, 4, v5
	v_mad_u64_u32 v[8:9], s[0:1], v114, s70, v[4:5]
	v_add_u32_e32 v5, 0x400, v120
	v_lshrrev_b32_e32 v5, 4, v5
	v_mad_u64_u32 v[10:11], s[0:1], v5, s70, v[4:5]
	v_add_u32_e32 v5, 0x600, v120
	v_lshrrev_b32_e32 v5, 4, v5
	s_waitcnt vmcnt(16)
	ds_write_b128 v6, v[50:53] offset:53248
	ds_write_b128 v8, v[54:57] offset:53248
	ds_write_b128 v10, v[58:61] offset:53248
	v_mad_u64_u32 v[10:11], s[0:1], v5, s70, v[4:5]
	s_movk_i32 s0, 0x8e
	s_nop 0
	v_mad_u32_u24 v4, v3, s0, v4
	v_lshl_add_u32 v5, v116, 1, v4
	v_lshl_add_u32 v4, v114, 1, v4
	v_cmp_lt_i32_e64 s[0:1], 63, v120
	ds_write_b128 v10, v[62:65] offset:53248
	ds_write_b128 v6, v[34:37]
	ds_write_b128 v6, v[38:41] offset:17408
	ds_write_b16 v5, v66 offset:34816
	ds_write_b16_d16_hi v5, v66 offset:34960
	ds_write_b16 v5, v67 offset:35104
	ds_write_b16_d16_hi v5, v67 offset:35248
	ds_write_b16 v5, v68 offset:35392
	ds_write_b16_d16_hi v5, v68 offset:35536
	ds_write_b16 v5, v69 offset:35680
	ds_write_b16_d16_hi v5, v69 offset:35824
	ds_write_b128 v8, v[42:45]
	ds_write_b128 v8, v[46:49] offset:17408
	ds_write_b16 v4, v70 offset:34816
	ds_write_b16_d16_hi v4, v70 offset:34960
	ds_write_b16 v4, v71 offset:35104
	ds_write_b16_d16_hi v4, v71 offset:35248
	ds_write_b16 v4, v72 offset:35392
	ds_write_b16_d16_hi v4, v72 offset:35536
	ds_write_b16 v4, v73 offset:35680
	ds_write_b16_d16_hi v4, v73 offset:35824
	s_and_saveexec_b64 s[4:5], s[0:1]
	s_xor_b64 s[4:5], exec, s[4:5]
	s_cbranch_execz .LBB0_620
	s_movk_i32 s3, 0xc0
	v_cmp_gt_u32_e32 vcc, s3, v120
	s_and_saveexec_b64 s[6:7], vcc
	s_cbranch_execz .LBB0_619
	v_readlane_b32 s3, v238, 34
	s_nop 1
	v_lshl_add_u32 v4, v120, 2, s3
	v_add_u32_e32 v4, 0xffffff00, v4
	ds_write_b32 v4, v121

.LBB0_627:
	s_andn2_saveexec_b64 s[0:1], s[0:1]
	s_cbranch_execz .LBB0_629
	s_ashr_i32 s7, s6, 31
	s_lshl_b64 s[6:7], s[6:7], 16
	s_add_u32 s6, s89, s6
	s_addc_u32 s7, s33, s7
	s_lshl_b32 s8, s11, 2
	s_add_u32 s6, s6, s8
	v_ashrrev_i32_e32 v121, 31, v120
	s_addc_u32 s7, s7, 0
	v_lshl_add_u64 v[2:3], v[120:121], 2, s[6:7]
	v_lshl_add_u64 v[4:5], s[4:5], 0, v[120:121]
	v_readlane_b32 s4, v238, 32
	v_add_co_u32_e32 v2, vcc, 0x6000, v2
	v_lshlrev_b64 v[4:5], 5, v[4:5]
	v_readlane_b32 s5, v238, 33
	v_addc_co_u32_e32 v3, vcc, 0, v3, vcc
	s_nop 0
	v_lshl_add_u64 v[4:5], s[4:5], 0, v[4:5]
	s_lshl_b32 s4, s10, 2
	s_mov_b32 s5, s83
	v_lshl_add_u64 v[4:5], v[4:5], 0, s[4:5]
	global_load_dword v121, v[2:3], off
	global_load_dword v107, v[4:5], off

; #define MLO_LOADV(UU) do { const int _bh = (UU) >> 8, _c = (UU) & 255, _b = _bh >> 2, _h = _bh & 3; const size_t _r0 = (size_t)_b * SEQ + _c * 64; \
;         _Pragma("unroll") for (int i = 0; i < 2; ++i) { const int id = tid + 512 * i, row = id >> 4, ch = id & 15; rv[i] = *(const u32x4*)(proj + (_r0 + row) * NIN + 2560 + _h * 128 + 8 * ch); } } while (0)
; __device__ __forceinline__ void ml_out_phase(const Args& a, LAS unsigned char* lds) {
;     ...
;     if (unit + G < 2048) MLO_LOADV(unit + G);
.LBB0_639:
	s_andn2_b64 vcc, exec, s[4:5]
	s_cbranch_vccnz .Lmlo_tail_last
	s_ashr_i32 s4, s2, 10
	s_ashr_i32 s5, s4, 31
	s_add_i32 s3, s93, s72
	s_lshl_b64 s[4:5], s[4:5], 14
	s_and_b32 s6, s3, 0x3fc0
	s_or_b32 s4, s4, s6
	v_lshl_add_u64 v[2:3], s[4:5], 0, v[116:117]
	v_mov_b64_e32 v[4:5], s[76:77]
	v_mad_u64_u32 v[6:7], s[6:7], v2, s90, v[4:5]
	v_mad_i32_i24 v7, v3, s90, v7
	s_and_b32 s6, s2, 0x300
	s_mov_b32 s7, s83
	v_lshl_add_u64 v[2:3], v[6:7], 0, s[6:7]
	v_lshl_add_u64 v[6:7], s[4:5], 0, v[114:115]
	v_mov_b32_e32 v119, v109
	v_mad_u64_u32 v[4:5], s[4:5], v6, s90, v[4:5]
	v_lshl_add_u64 v[2:3], v[2:3], 0, v[118:119]
	v_mad_i32_i24 v5, v7, s90, v5
	v_add_co_u32_e32 v2, vcc, s91, v2
	v_lshl_add_u64 v[4:5], v[4:5], 0, s[6:7]
	s_nop 0
	v_addc_co_u32_e32 v3, vcc, 0, v3, vcc
	v_lshl_add_u64 v[4:5], v[4:5], 0, v[118:119]
	v_add_co_u32_e32 v4, vcc, 0x1000, v4
	s_nop 1
	v_addc_co_u32_e32 v5, vcc, 0, v5, vcc
	global_load_dwordx4 v[66:69], v[2:3], off offset:1024
	global_load_dwordx4 v[70:73], v[4:5], off offset:1024
	s_branch .LBB0_615
.Lmlo_tail_last:
	s_waitcnt vmcnt(0)
	s_branch .LBB0_615
.LBB0_641:
	v_readlane_b32 s0, v238, 21
	v_readlane_b32 s1, v238, 22
	s_cmp_lt_i32 s1, 9
	s_cbranch_scc1 .LBB0_698
	v_readlane_b32 s0, v238, 23
	v_readlane_b32 s1, v238, 24
	s_xor_b64 s[0:1], s[0:1], -1
	s_andn2_b64 vcc, exec, s[0:1]
	v_cmp_eq_u32_e64 s[0:1], 0, v1
	s_cbranch_vccnz .LBB0_649
	s_and_saveexec_b64 s[2:3], s[0:1]
	s_cbranch_execz .LBB0_645
	s_add_i32 s4, 0, 0x23ff0
	v_mov_b32_e32 v2, 0
	v_mov_b32_e32 v3, s4
	s_add_i32 s4, 0, 0x23ff4
	ds_write_b32 v3, v2
	v_mov_b32_e32 v3, s4
	ds_write_b32 v3, v2
